# v14 + in-XCD start stagger for P1: workgroups with (blockIdx>>3)&1 enter the in-proj GEMM 3 us later, so the per-XCD output write bursts of the two halves do not coincide
# baseline (speedup 1.0000x reference)
.LBB0_190:
	s_lshr_b32 s98, s2, 3
	s_and_b32 s98, s98, 1
	s_mul_i32 s100, s98, 300
	s_memrealtime s[98:99]
	s_waitcnt lgkmcnt(0)
	s_add_u32 s100, s98, s100
.Lstx_p1c_loop:
	s_memrealtime s[98:99]
	s_waitcnt lgkmcnt(0)
	s_sub_u32 s101, s100, s98
	s_cmp_gt_i32 s101, 0
	s_cbranch_scc1 .Lstx_p1c_loop
	s_cmp_lt_i32 s26, 2
	s_mov_b64 s[72:73], s[80:81]
	s_cselect_b64 s[80:81], -1, 0
	s_and_b64 s[0:1], s[80:81], s[4:5]
	s_add_u32 s82, s24, 0x6345000
	s_addc_u32 s83, s25, 0
	s_add_u32 s76, s24, 0x118c5000
	s_addc_u32 s77, s25, 0
	s_lshr_b32 s4, s68, 8
	s_bfe_u32 s29, s68, 0x20006
	s_lshl_b32 s3, s4, 6
	v_writelane_b32 v248, s3, 17
	s_lshl_b32 s3, s29, 5
	s_ashr_i32 s12, s2, 31
	v_writelane_b32 v248, s3, 18
	s_lshr_b32 s3, s12, 29
	s_add_i32 s3, s2, s3
	s_ashr_i32 s5, s3, 3
	s_and_b32 s3, s3, -8
	s_lshl_b32 s31, s90, 10
	s_sub_i32 s3, s2, s3
	s_cmp_lt_i32 s3, 0
	v_writelane_b32 v248, s5, 19
	s_cselect_b64 s[6:7], -1, 0
	v_writelane_b32 v248, s6, 20
	s_cmp_gt_i32 s3, -1
	s_nop 0
	v_writelane_b32 v248, s7, 21
	v_writelane_b32 v248, s3, 22
	s_cselect_b64 s[6:7], -1, 0
	v_writelane_b32 v248, s6, 23
	s_cmp_eq_u32 s4, 1
	s_nop 0
	v_writelane_b32 v248, s7, 24
	v_writelane_b32 v248, s4, 25
	s_cselect_b64 s[4:5], -1, 0
	v_writelane_b32 v248, s4, 26
	s_cmpk_lt_u32 s68, 0x100
	s_nop 0
	v_writelane_b32 v248, s5, 27
	s_cselect_b64 s[4:5], -1, 0
	v_writelane_b32 v248, s4, 28
	s_ashr_i32 s13, s74, 31
	s_andn2_b64 vcc, exec, s[0:1]
	v_writelane_b32 v248, s5, 29
	v_writelane_b32 v248, s12, 30
	v_writelane_b32 v248, s13, 31
	v_writelane_b32 v248, s88, 32
	s_nop 1
	v_writelane_b32 v248, s89, 33
	v_writelane_b32 v248, s54, 34
	s_nop 1
	v_writelane_b32 v248, s55, 35
	v_writelane_b32 v248, s96, 36
	s_nop 1
	v_writelane_b32 v248, s97, 37
	s_cbranch_vccnz .LBB0_350
	s_cmpk_lt_i32 s2, 0x528
	s_cselect_b64 s[0:1], -1, 0
	s_cmpk_gt_i32 s2, 0x527
	v_mov_b32_e32 v12, v184
	s_movk_i32 s4, 0x400
	s_cbranch_scc1 .LBB0_193
	v_readlane_b32 s6, v248, 20
	v_readlane_b32 s7, v248, 21
	s_movk_i32 s3, 0xa6
	s_and_b64 s[6:7], s[6:7], exec
	s_cselect_b32 s3, s3, 0xa5
	v_readlane_b32 s5, v248, 22
	s_mul_i32 s3, s5, s3
	v_readlane_b32 s5, v248, 19
	s_add_i32 s3, s3, s5
	s_mul_hi_i32 s5, s3, 0x66666667
	s_lshr_b32 s6, s5, 31
	s_ashr_i32 s5, s5, 5
	s_add_i32 s5, s5, s6
	s_lshl_b32 s8, s5, 3
	s_sub_i32 s6, 0x84, s8
	s_min_u32 s9, s6, 8
	s_mulk_i32 s5, 0x50
	s_sub_i32 s3, s3, s5
	v_cvt_f32_ubyte0_e32 v1, s9
	v_cvt_f32_i32_e32 v0, s3
	v_rcp_iflag_f32_e32 v2, v1
	s_ashr_i32 s5, s3, 30
	s_or_b32 s5, s5, 1
	v_mul_f32_e32 v2, v0, v2
	v_trunc_f32_e32 v2, v2
	v_fma_f32 v0, -v2, v1, v0
	v_cvt_i32_f32_e32 v2, v2
	v_cmp_ge_f32_e64 s[6:7], |v0|, v1
	s_and_b64 s[6:7], s[6:7], exec
	s_cselect_b32 s5, s5, 0
	v_readfirstlane_b32 s6, v2
	s_add_i32 s5, s6, s5
	s_sext_i32_i8 s14, s5
	s_mul_i32 s5, s5, s9
	s_sub_i32 s3, s3, s5
	s_sext_i32_i8 s3, s3
	s_add_i32 s15, s8, s3
